# added: MLA attention epilogue OM bf16 rows stored row-contiguous (4 rows x 256B per store) on top of the row-contiguous O1 stores
# baseline (speedup 1.0000x reference)
; #define SBAR() __builtin_amdgcn_sched_barrier(0)
; __device__ __forceinline__ int crow(int r, int hi) { return (r & 3) + 8 * (r >> 2) + 4 * hi; }
; #define PVF(...) do { if constexpr (!MLA || ATT_PIPE_MLA) pv_pipe(__VA_ARGS__); else pv_d0(__VA_ARGS__); } while (0)
; template <int D0> __device__ __forceinline__ void pv_one(f32x16& od, int vb, bf16x8 pa0, bf16x8 pa1, bf16x8 pa2, bf16x8 pa3) {
;   const s16x4 l0 = tr_read<v_rd_off(D0, 0, 0)>(vb), h0 = tr_read<v_rd_off(D0, 0, 1)>(vb), l1 = tr_read<v_rd_off(D0, 1, 0)>(vb), h1 = tr_read<v_rd_off(D0, 1, 1)>(vb);
;   const s16x4 l2 = tr_read<v_rd_off(D0, 2, 0)>(vb), h2 = tr_read<v_rd_off(D0, 2, 1)>(vb), l3 = tr_read<v_rd_off(D0, 3, 0)>(vb), h3 = tr_read<v_rd_off(D0, 3, 1)>(vb);
;   asm volatile("s_waitcnt lgkmcnt(0)" ::: "memory"); SBAR();
;     ...
;   od = __builtin_amdgcn_mfma_f32_32x32x16_bf16(pa0, PK(l0, h0), od, 0, 0, 0);
;   od = __builtin_amdgcn_mfma_f32_32x32x16_bf16(pa1, PK(l1, h1), od, 0, 0, 0);
;   od = __builtin_amdgcn_mfma_f32_32x32x16_bf16(pa2, PK(l2, h2), od, 0, 0, 0);
;   od = __builtin_amdgcn_mfma_f32_32x32x16_bf16(pa3, PK(l3, h3), od, 0, 0, 0);
;     ...
; }
; __device__ __forceinline__ void pv_d0(f32x16* o, int vb, bf16x8 pa0, bf16x8 pa1, bf16x8 pa2, bf16x8 pa3) {
;   pv_one<0>(o[0], vb, pa0, pa1, pa2, pa3); pv_one<1>(o[1], vb, pa0, pa1, pa2, pa3); pv_one<2>(o[2], vb, pa0, pa1, pa2, pa3); pv_one<3>(o[3], vb, pa0, pa1, pa2, pa3);
; template <bool MLA> ...
;     ...
;   finishSM(pB0, pB1, alB, l_reg, pa0, pa1, pa2, pa3); SBAR();
;   PVF(o, vb0 + SHM_V, pa0, pa1, pa2, pa3);
;     ...
;   if (hi == 0) li_l[r32] = l_reg; asm volatile("s_waitcnt lgkmcnt(0)" ::: "memory");
; #pragma unroll
;   for (int r = 0; r < 16; ++r) rli[r] = __builtin_amdgcn_rcpf(li_l[crow(r, hi)]);
;   __syncthreads();
.LBB0_743:
	v_exp_f32_e32 v90, v98
	v_exp_f32_e32 v91, v99
	v_exp_f32_e32 v92, v100
	v_exp_f32_e32 v93, v101
	v_exp_f32_e32 v94, v102
	v_exp_f32_e32 v98, v66
	v_add_f32_e32 v66, 0, v90
	v_exp_f32_e32 v95, v103
	v_add_f32_e32 v66, v91, v66
	v_exp_f32_e32 v96, v104
	v_add_f32_e32 v66, v92, v66
	v_exp_f32_e32 v97, v105
	v_add_f32_e32 v66, v93, v66
	v_exp_f32_e32 v82, v106
	v_add_f32_e32 v66, v94, v66
	v_exp_f32_e32 v83, v107
	v_add_f32_e32 v66, v95, v66
	v_exp_f32_e32 v84, v108
	v_add_f32_e32 v66, v96, v66
	v_exp_f32_e32 v85, v109
	v_add_f32_e32 v66, v97, v66
	v_exp_f32_e32 v86, v110
	v_add_f32_e32 v66, v82, v66
	v_exp_f32_e32 v87, v111
	v_add_f32_e32 v66, v83, v66
	v_exp_f32_e32 v88, v112
	v_add_f32_e32 v66, v84, v66
	v_exp_f32_e32 v89, v113
	v_add_f32_e32 v66, v85, v66
	v_add_f32_e32 v66, v86, v66
	v_exp_f32_e32 v99, v67
	v_add_f32_e32 v66, v87, v66
	v_exp_f32_e32 v100, v68
	v_add_f32_e32 v66, v88, v66
	v_exp_f32_e32 v101, v69
	v_add_f32_e32 v66, v89, v66
	v_exp_f32_e32 v102, v70
	v_add_f32_e32 v66, v98, v66
	v_exp_f32_e32 v103, v71
	v_add_f32_e32 v66, v99, v66
	v_exp_f32_e32 v104, v72
	v_add_f32_e32 v66, v100, v66
	v_exp_f32_e32 v105, v73
	v_add_f32_e32 v66, v101, v66
	v_exp_f32_e32 v106, v74
	v_add_f32_e32 v66, v102, v66
	v_exp_f32_e32 v107, v75
	v_add_f32_e32 v66, v103, v66
	v_exp_f32_e32 v108, v76
	v_add_f32_e32 v66, v104, v66
	v_exp_f32_e32 v109, v77
	v_add_f32_e32 v66, v105, v66
	v_exp_f32_e32 v110, v78
	v_add_f32_e32 v66, v106, v66
	v_exp_f32_e32 v111, v79
	v_add_f32_e32 v66, v107, v66
	v_exp_f32_e32 v112, v80
	v_add_f32_e32 v66, v108, v66
	v_exp_f32_e32 v113, v81
	v_add_f32_e32 v66, v109, v66
	v_add_f32_e32 v66, v110, v66
	v_add_f32_e32 v66, v111, v66
	v_add_f32_e32 v66, v112, v66
	v_add_f32_e32 v66, v113, v66
	v_mov_b32_e32 v67, v66
	s_nop 1
	v_permlane32_swap_b32_e32 v66, v67
	v_cvt_pk_bf16_f32 v68, v90, v91
	v_cvt_pk_bf16_f32 v69, v92, v93
	v_cvt_pk_bf16_f32 v70, v94, v95
	v_cvt_pk_bf16_f32 v71, v96, v97
	v_cvt_pk_bf16_f32 v72, v82, v83
	v_cvt_pk_bf16_f32 v73, v84, v85
	v_cvt_pk_bf16_f32 v74, v86, v87
	v_cvt_pk_bf16_f32 v75, v88, v89
	v_cvt_pk_bf16_f32 v76, v98, v99
	v_cvt_pk_bf16_f32 v77, v100, v101
	v_cvt_pk_bf16_f32 v78, v102, v103
	v_cvt_pk_bf16_f32 v79, v104, v105
	v_cvt_pk_bf16_f32 v80, v106, v107
	v_cvt_pk_bf16_f32 v81, v108, v109
	v_cvt_pk_bf16_f32 v82, v110, v111
	v_cvt_pk_bf16_f32 v83, v112, v113
	v_permlane32_swap_b32_e32 v68, v70
	v_permlane32_swap_b32_e32 v69, v71
	v_permlane32_swap_b32_e32 v72, v74
	v_permlane32_swap_b32_e32 v73, v75
	v_permlane32_swap_b32_e32 v76, v78
	v_permlane32_swap_b32_e32 v77, v79
	v_permlane32_swap_b32_e32 v80, v82
	v_permlane32_swap_b32_e32 v81, v83
	ds_read_b64_tr_b16 v[84:85], v178 offset:0
	ds_read_b64_tr_b16 v[86:87], v178 offset:0x800
	ds_read_b64_tr_b16 v[88:89], v178 offset:0x1000
	ds_read_b64_tr_b16 v[90:91], v178 offset:0x1800
	ds_read_b64_tr_b16 v[92:93], v178 offset:0x2000
	ds_read_b64_tr_b16 v[94:95], v178 offset:0x2800
	ds_read_b64_tr_b16 v[96:97], v178 offset:0x3000
	ds_read_b64_tr_b16 v[98:99], v178 offset:0x3800
	s_waitcnt lgkmcnt(0)
	s_nop 0
	v_mfma_f32_32x32x16_bf16 v[2:17], v[68:71], v[84:87], v[2:17]
	ds_read_b64_tr_b16 v[84:85], v178 offset:0x200
	ds_read_b64_tr_b16 v[86:87], v178 offset:0xa00
	v_mfma_f32_32x32x16_bf16 v[2:17], v[72:75], v[88:91], v[2:17]
	ds_read_b64_tr_b16 v[88:89], v178 offset:0x1200
	ds_read_b64_tr_b16 v[90:91], v178 offset:0x1a00
	v_mfma_f32_32x32x16_bf16 v[2:17], v[76:79], v[92:95], v[2:17]
	ds_read_b64_tr_b16 v[92:93], v178 offset:0x2200
	ds_read_b64_tr_b16 v[94:95], v178 offset:0x2a00
	v_mfma_f32_32x32x16_bf16 v[2:17], v[80:83], v[96:99], v[2:17]
	ds_read_b64_tr_b16 v[96:97], v178 offset:0x3200
	ds_read_b64_tr_b16 v[98:99], v178 offset:0x3a00
	s_waitcnt lgkmcnt(0)
	v_mfma_f32_32x32x16_bf16 v[50:65], v[68:71], v[84:87], v[50:65]
	ds_read_b64_tr_b16 v[84:85], v178 offset:0x400
	ds_read_b64_tr_b16 v[86:87], v178 offset:0xc00
	v_mfma_f32_32x32x16_bf16 v[50:65], v[72:75], v[88:91], v[50:65]
	ds_read_b64_tr_b16 v[88:89], v178 offset:0x1400
	ds_read_b64_tr_b16 v[90:91], v178 offset:0x1c00
	v_mfma_f32_32x32x16_bf16 v[50:65], v[76:79], v[92:95], v[50:65]
	ds_read_b64_tr_b16 v[92:93], v178 offset:0x2400
	ds_read_b64_tr_b16 v[94:95], v178 offset:0x2c00
	v_mfma_f32_32x32x16_bf16 v[50:65], v[80:83], v[96:99], v[50:65]
	ds_read_b64_tr_b16 v[96:97], v178 offset:0x3400
	ds_read_b64_tr_b16 v[98:99], v178 offset:0x3c00
	s_waitcnt lgkmcnt(0)
	v_mfma_f32_32x32x16_bf16 v[34:49], v[68:71], v[84:87], v[34:49]
	ds_read_b64_tr_b16 v[84:85], v178 offset:0x600
	ds_read_b64_tr_b16 v[86:87], v178 offset:0xe00
	v_mfma_f32_32x32x16_bf16 v[34:49], v[72:75], v[88:91], v[34:49]
	ds_read_b64_tr_b16 v[88:89], v178 offset:0x1600
	ds_read_b64_tr_b16 v[90:91], v178 offset:0x1e00
	v_mfma_f32_32x32x16_bf16 v[34:49], v[76:79], v[92:95], v[34:49]
	ds_read_b64_tr_b16 v[92:93], v178 offset:0x2600
	ds_read_b64_tr_b16 v[94:95], v178 offset:0x2e00
	v_mfma_f32_32x32x16_bf16 v[34:49], v[80:83], v[96:99], v[34:49]
	ds_read_b64_tr_b16 v[96:97], v178 offset:0x3600
	ds_read_b64_tr_b16 v[98:99], v178 offset:0x3e00
	s_waitcnt lgkmcnt(0)
	v_mfma_f32_32x32x16_bf16 v[18:33], v[68:71], v[84:87], v[18:33]
	v_mfma_f32_32x32x16_bf16 v[18:33], v[72:75], v[88:91], v[18:33]
	v_mfma_f32_32x32x16_bf16 v[18:33], v[76:79], v[92:95], v[18:33]
	v_mfma_f32_32x32x16_bf16 v[18:33], v[80:83], v[96:99], v[18:33]
	s_and_saveexec_b64 s[8:9], s[38:39]
	v_add_f32_e32 v68, v114, v115
	v_fmac_f32_e32 v68, v177, v150
	v_add_f32_e32 v66, v66, v67
	v_fmac_f32_e32 v66, v68, v116
	ds_write_b32 v176, v66
	s_or_b64 exec, exec, s[8:9]
	s_waitcnt lgkmcnt(0)
	v_add_u32_e32 v74, s10, v160
	ds_read_b128 v[66:69], v74
	ds_read_b128 v[70:73], v74 offset:32
	s_and_b32 s8, s28, 0xf00
	s_add_u32 s8, s8, s14
	s_addc_u32 s9, 0, s15
	s_waitcnt lgkmcnt(1)
	v_rcp_f32_e32 v75, v66
	v_rcp_f32_e32 v76, v67
	v_rcp_f32_e32 v77, v68
	v_rcp_f32_e32 v78, v69
	s_waitcnt lgkmcnt(0)
	v_rcp_f32_e32 v79, v70
	ds_read_b128 v[66:69], v74 offset:64
	v_rcp_f32_e32 v80, v71
	v_rcp_f32_e32 v81, v72
	v_rcp_f32_e32 v82, v73
	ds_read_b128 v[70:73], v74 offset:96
	v_mov_b32_e32 v74, v0
	s_waitcnt lgkmcnt(0)
	s_barrier
; __device__ __forceinline__ u32x4 pack8(const f32x4 a, const f32x4 b) { u32x4 w; w.x = cvt_pk(a[0], a[1]); w.y = cvt_pk(a[2], a[3]); w.z = cvt_pk(b[0], b[1]); w.w = cvt_pk(b[2], b[3]); return w; }
; __device__ __forceinline__ int crow(int r, int hi) { return (r & 3) + 8 * (r >> 2) + 4 * hi; }
; __device__ __forceinline__ int opaque_tid() { int t = threadIdx.x; asm volatile("" : "+v"(t)); return t; }
; template <int MODE> __device__ __forceinline__ void attn_epilogue(char* lds, const att::f32x16 (&o)[4], const float (&rli)[16], float* o1, bf16raw* ob, float lam, float post, const float* gs) {
;     const int tid_ = opaque_tid(); const int lane = tid_ & 63, wave = tid_ >> 6, r32 = lane & 31, hi = lane >> 5;
;     float* st = (float*)(lds + wave * ATT_STAGE);
; #pragma unroll
;     for (int r = 0; r < 16; ++r) { const int orow = att::crow(r, hi);
; #pragma unroll
;         for (int d0 = 0; d0 < 4; ++d0) st[orow * 132 + d0 * 32 + r32] = o[d0][r] * rli[r]; }
;     asm volatile("s_waitcnt lgkmcnt(0)" ::: "memory");
;     float* sr = st + r32 * 132 + 64 * hi;
;     const size_t goff = (size_t)r32 * 1024 + 64 * hi, boff = (size_t)r32 * 2048 + 64 * hi;
;     if constexpr (MODE == 0) {
; #pragma unroll 4
;         for (int j = 0; j < 16; ++j) *(f32x4*)(o1 + goff + 4 * j) = *(const f32x4*)(sr + 4 * j);
;     } else if constexpr (MODE == 2) {
; #pragma unroll 4
;         for (int j = 0; j < 8; ++j) *(ep::u32x4*)(ob + boff + 8 * j) = ep::pack8(*(const f32x4*)(sr + 8 * j), *(const f32x4*)(sr + 8 * j + 4));
	v_mul_f32_e32 v2, v2, v75
	v_lshrrev_b32_e32 v83, 6, v74
	v_and_b32_e32 v84, 31, v74
	v_bfe_u32 v74, v74, 5, 1
	v_mul_lo_u32 v83, v83, s75
	v_add_u32_e32 v83, 0, v83
	v_lshlrev_b32_e32 v85, 2, v84
	v_mul_u32_u24_e32 v86, 0x840, v74
	v_add3_u32 v85, v83, v85, v86
	v_mul_f32_e32 v50, v50, v75
	ds_write2_b32 v85, v2, v50 offset1:32
	v_mul_f32_e32 v2, v34, v75
	v_mul_f32_e32 v18, v18, v75
	ds_write2_b32 v85, v2, v18 offset0:64 offset1:96
	v_mul_f32_e32 v2, v3, v76
	v_mul_f32_e32 v3, v51, v76
	ds_write2_b32 v85, v2, v3 offset0:132 offset1:164
	v_mul_f32_e32 v2, v35, v76
	v_mul_f32_e32 v3, v19, v76
	ds_write2_b32 v85, v2, v3 offset0:196 offset1:228
	v_mul_f32_e32 v2, v4, v77
	v_mul_f32_e32 v3, v52, v77
	v_add_u32_e32 v4, 0x400, v85
	ds_write2_b32 v4, v2, v3 offset0:8 offset1:40
	v_mul_f32_e32 v2, v36, v77
	v_mul_f32_e32 v3, v20, v77
	ds_write2_b32 v4, v2, v3 offset0:72 offset1:104
	v_mul_f32_e32 v2, v5, v78
	v_mul_f32_e32 v3, v53, v78
	ds_write2_b32 v4, v2, v3 offset0:140 offset1:172
	v_mul_f32_e32 v2, v37, v78
	v_mul_f32_e32 v3, v21, v78
	ds_write2_b32 v4, v2, v3 offset0:204 offset1:236
	v_mul_f32_e32 v2, v6, v79
	v_mul_f32_e32 v3, v54, v79
	v_add_u32_e32 v4, 0x1000, v85
	ds_write2_b32 v4, v2, v3 offset0:32 offset1:64
	v_mul_f32_e32 v2, v38, v79
	v_mul_f32_e32 v3, v22, v79
	ds_write2_b32 v4, v2, v3 offset0:96 offset1:128
	v_mul_f32_e32 v2, v7, v80
	v_mul_f32_e32 v3, v55, v80
	ds_write2_b32 v4, v2, v3 offset0:164 offset1:196
	v_mul_f32_e32 v2, v39, v80
	v_mul_f32_e32 v3, v23, v80
	v_add_u32_e32 v4, 0x1200, v85
	v_rcp_f32_e32 v66, v66
	ds_write2_b32 v4, v2, v3 offset0:100 offset1:132
	v_mul_f32_e32 v2, v8, v81
	v_mul_f32_e32 v3, v56, v81
	v_add_u32_e32 v4, 0x1400, v85
	ds_write2_b32 v4, v2, v3 offset0:40 offset1:72
	v_mul_f32_e32 v2, v40, v81
	v_mul_f32_e32 v3, v24, v81
	v_rcp_f32_e32 v67, v67
	ds_write2_b32 v4, v2, v3 offset0:104 offset1:136
	v_mul_f32_e32 v2, v9, v82
	v_mul_f32_e32 v3, v57, v82
	ds_write2_b32 v4, v2, v3 offset0:172 offset1:204
	v_mul_f32_e32 v2, v41, v82
	v_mul_f32_e32 v3, v25, v82
	v_add_u32_e32 v4, 0x1600, v85
	v_rcp_f32_e32 v68, v68
	ds_write2_b32 v4, v2, v3 offset0:108 offset1:140
	v_mul_f32_e32 v2, v10, v66
	v_mul_f32_e32 v3, v58, v66
	v_add_u32_e32 v4, 0x2000, v85
	ds_write2_b32 v4, v2, v3 offset0:64 offset1:96
	v_mul_f32_e32 v2, v42, v66
	v_mul_f32_e32 v3, v26, v66
	v_rcp_f32_e32 v69, v69
	ds_write2_b32 v4, v2, v3 offset0:128 offset1:160
	v_mul_f32_e32 v2, v11, v67
	v_mul_f32_e32 v3, v59, v67
	ds_write2_b32 v4, v2, v3 offset0:196 offset1:228
	v_mul_f32_e32 v2, v43, v67
	v_mul_f32_e32 v3, v27, v67
	v_add_u32_e32 v4, 0x2400, v85
	v_rcp_f32_e32 v70, v70
	ds_write2_b32 v4, v2, v3 offset0:4 offset1:36
	v_mul_f32_e32 v2, v12, v68
	v_mul_f32_e32 v3, v60, v68
	ds_write2_b32 v4, v2, v3 offset0:72 offset1:104
	v_mul_f32_e32 v2, v44, v68
	v_mul_f32_e32 v3, v28, v68
	v_rcp_f32_e32 v71, v71
	ds_write2_b32 v4, v2, v3 offset0:136 offset1:168
	v_mul_f32_e32 v2, v13, v69
	v_mul_f32_e32 v3, v61, v69
	ds_write2_b32 v4, v2, v3 offset0:204 offset1:236
	v_mul_f32_e32 v2, v45, v69
	v_mul_f32_e32 v3, v29, v69
	v_add_u32_e32 v4, 0x2800, v85
	v_rcp_f32_e32 v72, v72
	ds_write2_b32 v4, v2, v3 offset0:12 offset1:44
	v_mul_f32_e32 v2, v14, v70
	v_mul_f32_e32 v3, v62, v70
	v_add_u32_e32 v4, 0x3000, v85
	ds_write2_b32 v4, v2, v3 offset0:96 offset1:128
	v_mul_f32_e32 v2, v46, v70
	v_mul_f32_e32 v3, v30, v70
	v_rcp_f32_e32 v73, v73
	ds_write2_b32 v4, v2, v3 offset0:160 offset1:192
	v_mul_f32_e32 v2, v15, v71
	v_mul_f32_e32 v3, v63, v71
	v_add_u32_e32 v4, 0x3200, v85
	ds_write2_b32 v4, v2, v3 offset0:100 offset1:132
	v_mul_f32_e32 v2, v47, v71
	v_mul_f32_e32 v3, v31, v71
	v_add_u32_e32 v4, 0x3400, v85
	ds_write2_b32 v4, v2, v3 offset0:36 offset1:68
	v_mul_f32_e32 v2, v16, v72
	v_mul_f32_e32 v3, v64, v72
	ds_write2_b32 v4, v2, v3 offset0:104 offset1:136
	v_mul_f32_e32 v2, v48, v72
	v_mul_f32_e32 v3, v32, v72
	ds_write2_b32 v4, v2, v3 offset0:168 offset1:200
	v_mul_f32_e32 v2, v17, v73
	v_mul_f32_e32 v3, v65, v73
	v_add_u32_e32 v4, 0x3600, v85
	ds_write2_b32 v4, v2, v3 offset0:108 offset1:140
	v_mul_f32_e32 v2, v49, v73
	v_mul_f32_e32 v3, v33, v73
	v_add_u32_e32 v4, 0x3800, v85
	ds_write2_b32 v4, v2, v3 offset0:44 offset1:76
	v_lshrrev_b32_e32 v2, 4, v84
	v_lshl_or_b32 v2, v74, 1, v2
	v_and_b32_e32 v3, 15, v84
	v_mul_u32_u24_e32 v4, 0x210, v2
	v_lshl_add_u32 v4, v3, 5, v4
	v_add_u32_e32 v4, v83, v4
	v_lshlrev_b32_e32 v5, 4, v3
	v_lshl_or_b32 v160, v2, 12, v5
	v_lshl_add_u64 v[2:3], s[8:9], 0, v[154:155]
	v_lshlrev_b64 v[2:3], 12, v[2:3]
	s_waitcnt lgkmcnt(0)
; __device__ __forceinline__ u32x4 pack8(const f32x4 a, const f32x4 b) { u32x4 w; w.x = cvt_pk(a[0], a[1]); w.y = cvt_pk(a[2], a[3]); w.z = cvt_pk(b[0], b[1]); w.w = cvt_pk(b[2], b[3]); return w; }
; template <int MODE> __device__ __forceinline__ void attn_epilogue(char* lds, const att::f32x16 (&o)[4], const float (&rli)[16], float* o1, bf16raw* ob, float lam, float post, const float* gs) {
;     ...
;     const size_t goff = (size_t)r32 * 1024 + 64 * hi, boff = (size_t)r32 * 2048 + 64 * hi;
;     if constexpr (MODE == 0) {
; #pragma unroll 4
;         for (int j = 0; j < 16; ++j) *(f32x4*)(o1 + goff + 4 * j) = *(const f32x4*)(sr + 4 * j);
;     } else if constexpr (MODE == 2) {
; #pragma unroll 4
;         for (int j = 0; j < 8; ++j) *(ep::u32x4*)(ob + boff + 8 * j) = ep::pack8(*(const f32x4*)(sr + 8 * j), *(const f32x4*)(sr + 8 * j + 4));
	v_lshl_or_b32 v2, s30, 8, v2
	v_lshl_add_u64 v[2:3], v[2:3], 0, v[160:161]
	v_lshl_add_u64 v[2:3], s[0:1], 0, v[2:3]
	s_mov_b32 s98, 0x4000
	s_mov_b32 s99, 0
	ds_read_b128 v[6:9], v4
	ds_read_b128 v[10:13], v4 offset:16
	ds_read_b128 v[14:17], v4 offset:2112
	ds_read_b128 v[18:21], v4 offset:2128
	s_waitcnt lgkmcnt(3)
	v_cvt_pk_bf16_f32 v6, v6, v7
	v_cvt_pk_bf16_f32 v7, v8, v9
	s_waitcnt lgkmcnt(2)
	v_cvt_pk_bf16_f32 v8, v10, v11
	v_cvt_pk_bf16_f32 v9, v12, v13
	global_store_dwordx4 v[2:3], v[6:9], off offset:-32
	s_nop 0
	v_lshl_add_u64 v[2:3], v[2:3], 0, s[98:99]
	s_waitcnt lgkmcnt(1)
	v_cvt_pk_bf16_f32 v6, v14, v15
	v_cvt_pk_bf16_f32 v7, v16, v17
	s_waitcnt lgkmcnt(0)
	v_cvt_pk_bf16_f32 v8, v18, v19
	v_cvt_pk_bf16_f32 v9, v20, v21
	global_store_dwordx4 v[2:3], v[6:9], off offset:-32
	s_nop 0
	v_lshl_add_u64 v[2:3], v[2:3], 0, s[98:99]
	ds_read_b128 v[6:9], v4 offset:4224
	ds_read_b128 v[10:13], v4 offset:4240
	ds_read_b128 v[14:17], v4 offset:6336
	ds_read_b128 v[18:21], v4 offset:6352
	s_waitcnt lgkmcnt(3)
	v_cvt_pk_bf16_f32 v6, v6, v7
	v_cvt_pk_bf16_f32 v7, v8, v9
	s_waitcnt lgkmcnt(2)
	v_cvt_pk_bf16_f32 v8, v10, v11
	v_cvt_pk_bf16_f32 v9, v12, v13
	global_store_dwordx4 v[2:3], v[6:9], off offset:-32
	s_nop 0
	v_lshl_add_u64 v[2:3], v[2:3], 0, s[98:99]
	s_waitcnt lgkmcnt(1)
	v_cvt_pk_bf16_f32 v6, v14, v15
	v_cvt_pk_bf16_f32 v7, v16, v17
	s_waitcnt lgkmcnt(0)
	v_cvt_pk_bf16_f32 v8, v18, v19
	v_cvt_pk_bf16_f32 v9, v20, v21
	global_store_dwordx4 v[2:3], v[6:9], off offset:-32
	s_nop 0
	v_lshl_add_u64 v[2:3], v[2:3], 0, s[98:99]
	ds_read_b128 v[6:9], v4 offset:8448
	ds_read_b128 v[10:13], v4 offset:8464
	ds_read_b128 v[14:17], v4 offset:10560
	ds_read_b128 v[18:21], v4 offset:10576
	s_waitcnt lgkmcnt(3)
	v_cvt_pk_bf16_f32 v6, v6, v7
	v_cvt_pk_bf16_f32 v7, v8, v9
	s_waitcnt lgkmcnt(2)
	v_cvt_pk_bf16_f32 v8, v10, v11
	v_cvt_pk_bf16_f32 v9, v12, v13
	global_store_dwordx4 v[2:3], v[6:9], off offset:-32
	s_nop 0
	v_lshl_add_u64 v[2:3], v[2:3], 0, s[98:99]
	s_waitcnt lgkmcnt(1)
	v_cvt_pk_bf16_f32 v6, v14, v15
	v_cvt_pk_bf16_f32 v7, v16, v17
	s_waitcnt lgkmcnt(0)
	v_cvt_pk_bf16_f32 v8, v18, v19
	v_cvt_pk_bf16_f32 v9, v20, v21
	global_store_dwordx4 v[2:3], v[6:9], off offset:-32
	s_nop 0
	v_lshl_add_u64 v[2:3], v[2:3], 0, s[98:99]
	ds_read_b128 v[6:9], v4 offset:12672
	ds_read_b128 v[10:13], v4 offset:12688
	ds_read_b128 v[14:17], v4 offset:14784
	ds_read_b128 v[18:21], v4 offset:14800
	s_waitcnt lgkmcnt(3)
	v_cvt_pk_bf16_f32 v6, v6, v7
	v_cvt_pk_bf16_f32 v7, v8, v9
	s_waitcnt lgkmcnt(2)
	v_cvt_pk_bf16_f32 v8, v10, v11
	v_cvt_pk_bf16_f32 v9, v12, v13
	global_store_dwordx4 v[2:3], v[6:9], off offset:-32
	s_nop 0
	v_lshl_add_u64 v[2:3], v[2:3], 0, s[98:99]
	s_waitcnt lgkmcnt(1)
	v_cvt_pk_bf16_f32 v6, v14, v15
	v_cvt_pk_bf16_f32 v7, v16, v17
	s_waitcnt lgkmcnt(0)
	v_cvt_pk_bf16_f32 v8, v18, v19
	v_cvt_pk_bf16_f32 v9, v20, v21
	global_store_dwordx4 v[2:3], v[6:9], off offset:-32
	s_nop 0
	v_lshl_add_u64 v[2:3], v[2:3], 0, s[98:99]
	s_add_i32 s4, s4, s73
	s_add_i32 s28, s28, s29
	s_cmpk_gt_i32 s4, 0x1ff
	s_barrier
	s_cbranch_scc0 .LBB0_722
	s_branch .LBB0_749
